# P7 final-norm epilogue: out f32 stores as full 128B lines (lane-pair DPP exchange, 8 rows x 128B per store), on top of the GEMM3 full-line epilogue
# speedup vs baseline: 1.0925x; 1.0018x over previous
; __device__ __forceinline__ void st_bf16x8(bf16_t* p, const f32x4 a, const f32x4 b) { uint4 o; o.x = cvt_pk_bf16(a[0], a[1]); o.y = cvt_pk_bf16(a[2], a[3]); o.z = cvt_pk_bf16(b[0], b[1]); o.w = cvt_pk_bf16(b[2], b[3]); *(uint4*)p = o; }
;     __device__ __forceinline__ void fused(f32x4 (&acc)[2][2][4][2], const Unit& u, int wr, int wc, int fr, int fq, float* smem) const {
;     ...
;         __syncthreads();
; #pragma unroll
;         for (int ai = 0; ai < 2; ++ai)
; #pragma unroll
;             for (int m = 0; m < 4; ++m) { const int rl = rl0 + ai * HALF + m * 16; const size_t ro = (size_t)(u.pm * BM + rl) * DM; const float r = rsv[rl];
; #pragma unroll
;                 for (int bj = 0; bj < 2; ++bj) { const int c = cb + bj * HALF; const f32x4 v0 = acc[ai][bj][m][0], v1 = acc[ai][bj][m][1];
;                     if (MODE == 0) { st_bf16x8(X1 + ro + c, v0, v1); st_bf16x8(H + ro + c, v0 * r * gs[bj][0] + sh[bj][0], v1 * r * gs[bj][1] + sh[bj][1]); }
;                     else { *(f32x4*)(out + ro + c) = v0 * r * gs[bj][0]; *(f32x4*)(out + ro + c + 4) = v1 * r * gs[bj][1]; } } }
.LBB0_817:
	s_or_b64 exec, exec, s[4:5]
	v_lshl_add_u32 v80, v184, 2, 16
	v_add_u32_e32 v128, 0x1000, v80
	s_waitcnt lgkmcnt(0)
	s_barrier
	ds_read2_b32 v[186:187], v128 offset1:16
	ds_read2_b32 v[188:189], v128 offset0:32 offset1:48
	ds_read2_b32 v[190:191], v128 offset0:128 offset1:144
	ds_read2_b32 v[192:193], v128 offset0:160 offset1:176
	v_and_b32_e32 v142, 1, v168
	v_and_b32_e32 v196, -2, v168
	v_mov_b32_e32 v197, v169
	v_lshlrev_b64 v[140:141], 12, v[196:197]
	v_lshl_add_u64 v[140:141], s[56:57], 0, v[140:141]
	v_lshlrev_b64 v[194:195], 2, v[170:171]
	v_lshl_add_u64 v[140:141], v[140:141], 0, v[194:195]
	v_lshlrev_b32_e32 v142, 4, v142
	v_add_u32_e32 v142, 0x800, v142
	v_mov_b32_e32 v143, 0
	v_lshl_add_u64 v[140:141], v[140:141], 0, v[142:143]
	s_mov_b32 s8, 0x55555555
	s_mov_b32 s9, 0x55555555
	s_mov_b32 s10, 0xaaaaaaaa
	s_mov_b32 s11, 0xaaaaaaaa
	s_mov_b64 s[12:13], 0x10000
	s_mov_b64 s[14:15], 0x50000
	v_mov_b32_e32 v199, 0
	s_waitcnt vmcnt(0) lgkmcnt(0)
	v_mov_b32_e32 v198, v186
	v_pk_mul_f32 v[124:125], v[124:125], v[198:199] op_sel_hi:[1,0]
	v_pk_mul_f32 v[126:127], v[126:127], v[198:199] op_sel_hi:[1,0]
	v_pk_mul_f32 v[120:121], v[120:121], v[198:199] op_sel_hi:[1,0]
	v_pk_mul_f32 v[122:123], v[122:123], v[198:199] op_sel_hi:[1,0]
	v_pk_mul_f32 v[124:125], v[12:13], v[124:125]
	v_pk_mul_f32 v[126:127], v[14:15], v[126:127]
	v_pk_mul_f32 v[120:121], v[8:9], v[120:121]
	v_pk_mul_f32 v[122:123], v[10:11], v[122:123]
	s_mov_b64 vcc, s[8:9]
	s_nop 0
	v_cndmask_b32_dpp v132, v120, v124, vcc quad_perm:[1,0,3,2] row_mask:0xf bank_mask:0xf
	v_cndmask_b32_dpp v133, v121, v125, vcc quad_perm:[1,0,3,2] row_mask:0xf bank_mask:0xf
	v_cndmask_b32_dpp v134, v122, v126, vcc quad_perm:[1,0,3,2] row_mask:0xf bank_mask:0xf
	v_cndmask_b32_dpp v135, v123, v127, vcc quad_perm:[1,0,3,2] row_mask:0xf bank_mask:0xf
	s_mov_b64 vcc, s[10:11]
	v_cndmask_b32_dpp v136, v124, v120, vcc quad_perm:[1,0,3,2] row_mask:0xf bank_mask:0xf
	v_cndmask_b32_dpp v137, v125, v121, vcc quad_perm:[1,0,3,2] row_mask:0xf bank_mask:0xf
	v_cndmask_b32_dpp v138, v126, v122, vcc quad_perm:[1,0,3,2] row_mask:0xf bank_mask:0xf
	v_cndmask_b32_dpp v139, v127, v123, vcc quad_perm:[1,0,3,2] row_mask:0xf bank_mask:0xf
	global_store_dwordx4 v[140:141], v[132:135], off offset:-2048
	global_store_dwordx4 v[140:141], v[136:139], off offset:2048
	v_pk_mul_f32 v[116:117], v[116:117], v[198:199] op_sel_hi:[1,0]
	v_pk_mul_f32 v[118:119], v[118:119], v[198:199] op_sel_hi:[1,0]
	v_pk_mul_f32 v[112:113], v[112:113], v[198:199] op_sel_hi:[1,0]
	v_pk_mul_f32 v[114:115], v[114:115], v[198:199] op_sel_hi:[1,0]
	v_pk_mul_f32 v[116:117], v[4:5], v[116:117]
	v_pk_mul_f32 v[118:119], v[6:7], v[118:119]
	v_pk_mul_f32 v[112:113], v[0:1], v[112:113]
	v_pk_mul_f32 v[114:115], v[2:3], v[114:115]
	s_mov_b64 vcc, s[8:9]
	s_nop 0
	v_cndmask_b32_dpp v132, v112, v116, vcc quad_perm:[1,0,3,2] row_mask:0xf bank_mask:0xf
	v_cndmask_b32_dpp v133, v113, v117, vcc quad_perm:[1,0,3,2] row_mask:0xf bank_mask:0xf
	v_cndmask_b32_dpp v134, v114, v118, vcc quad_perm:[1,0,3,2] row_mask:0xf bank_mask:0xf
	v_cndmask_b32_dpp v135, v115, v119, vcc quad_perm:[1,0,3,2] row_mask:0xf bank_mask:0xf
	s_mov_b64 vcc, s[10:11]
	v_cndmask_b32_dpp v136, v116, v112, vcc quad_perm:[1,0,3,2] row_mask:0xf bank_mask:0xf
	v_cndmask_b32_dpp v137, v117, v113, vcc quad_perm:[1,0,3,2] row_mask:0xf bank_mask:0xf
	v_cndmask_b32_dpp v138, v118, v114, vcc quad_perm:[1,0,3,2] row_mask:0xf bank_mask:0xf
	v_cndmask_b32_dpp v139, v119, v115, vcc quad_perm:[1,0,3,2] row_mask:0xf bank_mask:0xf
	global_store_dwordx4 v[140:141], v[132:135], off offset:-1536
	global_store_dwordx4 v[140:141], v[136:139], off offset:2560
	v_lshl_add_u64 v[140:141], v[140:141], 0, s[12:13]
	v_mov_b32_e32 v198, v187
	v_pk_mul_f32 v[108:109], v[108:109], v[198:199] op_sel_hi:[1,0]
	v_pk_mul_f32 v[110:111], v[110:111], v[198:199] op_sel_hi:[1,0]
	v_pk_mul_f32 v[104:105], v[104:105], v[198:199] op_sel_hi:[1,0]
	v_pk_mul_f32 v[106:107], v[106:107], v[198:199] op_sel_hi:[1,0]
	v_pk_mul_f32 v[108:109], v[12:13], v[108:109]
	v_pk_mul_f32 v[110:111], v[14:15], v[110:111]
	v_pk_mul_f32 v[104:105], v[8:9], v[104:105]
	v_pk_mul_f32 v[106:107], v[10:11], v[106:107]
	s_mov_b64 vcc, s[8:9]
	s_nop 0
	v_cndmask_b32_dpp v132, v104, v108, vcc quad_perm:[1,0,3,2] row_mask:0xf bank_mask:0xf
	v_cndmask_b32_dpp v133, v105, v109, vcc quad_perm:[1,0,3,2] row_mask:0xf bank_mask:0xf
	v_cndmask_b32_dpp v134, v106, v110, vcc quad_perm:[1,0,3,2] row_mask:0xf bank_mask:0xf
	v_cndmask_b32_dpp v135, v107, v111, vcc quad_perm:[1,0,3,2] row_mask:0xf bank_mask:0xf
	s_mov_b64 vcc, s[10:11]
	v_cndmask_b32_dpp v136, v108, v104, vcc quad_perm:[1,0,3,2] row_mask:0xf bank_mask:0xf
	v_cndmask_b32_dpp v137, v109, v105, vcc quad_perm:[1,0,3,2] row_mask:0xf bank_mask:0xf
	v_cndmask_b32_dpp v138, v110, v106, vcc quad_perm:[1,0,3,2] row_mask:0xf bank_mask:0xf
	v_cndmask_b32_dpp v139, v111, v107, vcc quad_perm:[1,0,3,2] row_mask:0xf bank_mask:0xf
	global_store_dwordx4 v[140:141], v[132:135], off offset:-2048
	global_store_dwordx4 v[140:141], v[136:139], off offset:2048
	v_pk_mul_f32 v[100:101], v[100:101], v[198:199] op_sel_hi:[1,0]
	v_pk_mul_f32 v[102:103], v[102:103], v[198:199] op_sel_hi:[1,0]
	v_pk_mul_f32 v[96:97], v[96:97], v[198:199] op_sel_hi:[1,0]
	v_pk_mul_f32 v[98:99], v[98:99], v[198:199] op_sel_hi:[1,0]
	v_pk_mul_f32 v[100:101], v[4:5], v[100:101]
	v_pk_mul_f32 v[102:103], v[6:7], v[102:103]
	v_pk_mul_f32 v[96:97], v[0:1], v[96:97]
	v_pk_mul_f32 v[98:99], v[2:3], v[98:99]
	s_mov_b64 vcc, s[8:9]
	s_nop 0
	v_cndmask_b32_dpp v132, v96, v100, vcc quad_perm:[1,0,3,2] row_mask:0xf bank_mask:0xf
; __device__ __forceinline__ void st_bf16x8(bf16_t* p, const f32x4 a, const f32x4 b) { uint4 o; o.x = cvt_pk_bf16(a[0], a[1]); o.y = cvt_pk_bf16(a[2], a[3]); o.z = cvt_pk_bf16(b[0], b[1]); o.w = cvt_pk_bf16(b[2], b[3]); *(uint4*)p = o; }
;     __device__ __forceinline__ void fused(f32x4 (&acc)[2][2][4][2], const Unit& u, int wr, int wc, int fr, int fq, float* smem) const {
;     ...
; #pragma unroll
;         for (int ai = 0; ai < 2; ++ai)
; #pragma unroll
;             for (int m = 0; m < 4; ++m) { const int rl = rl0 + ai * HALF + m * 16; const size_t ro = (size_t)(u.pm * BM + rl) * DM; const float r = rsv[rl];
; #pragma unroll
;                 for (int bj = 0; bj < 2; ++bj) { const int c = cb + bj * HALF; const f32x4 v0 = acc[ai][bj][m][0], v1 = acc[ai][bj][m][1];
;                     if (MODE == 0) { st_bf16x8(X1 + ro + c, v0, v1); st_bf16x8(H + ro + c, v0 * r * gs[bj][0] + sh[bj][0], v1 * r * gs[bj][1] + sh[bj][1]); }
;                     else { *(f32x4*)(out + ro + c) = v0 * r * gs[bj][0]; *(f32x4*)(out + ro + c + 4) = v1 * r * gs[bj][1]; } } }
	v_cndmask_b32_dpp v133, v97, v101, vcc quad_perm:[1,0,3,2] row_mask:0xf bank_mask:0xf
	v_cndmask_b32_dpp v134, v98, v102, vcc quad_perm:[1,0,3,2] row_mask:0xf bank_mask:0xf
	v_cndmask_b32_dpp v135, v99, v103, vcc quad_perm:[1,0,3,2] row_mask:0xf bank_mask:0xf
	s_mov_b64 vcc, s[10:11]
	v_cndmask_b32_dpp v136, v100, v96, vcc quad_perm:[1,0,3,2] row_mask:0xf bank_mask:0xf
	v_cndmask_b32_dpp v137, v101, v97, vcc quad_perm:[1,0,3,2] row_mask:0xf bank_mask:0xf
	v_cndmask_b32_dpp v138, v102, v98, vcc quad_perm:[1,0,3,2] row_mask:0xf bank_mask:0xf
	v_cndmask_b32_dpp v139, v103, v99, vcc quad_perm:[1,0,3,2] row_mask:0xf bank_mask:0xf
	global_store_dwordx4 v[140:141], v[132:135], off offset:-1536
	global_store_dwordx4 v[140:141], v[136:139], off offset:2560
	v_lshl_add_u64 v[140:141], v[140:141], 0, s[12:13]
	v_mov_b32_e32 v198, v188
	v_pk_mul_f32 v[152:153], v[152:153], v[198:199] op_sel_hi:[1,0]
	v_pk_mul_f32 v[94:95], v[94:95], v[198:199] op_sel_hi:[1,0]
	v_pk_mul_f32 v[154:155], v[154:155], v[198:199] op_sel_hi:[1,0]
	v_pk_mul_f32 v[92:93], v[92:93], v[198:199] op_sel_hi:[1,0]
	v_pk_mul_f32 v[152:153], v[12:13], v[152:153]
	v_pk_mul_f32 v[94:95], v[14:15], v[94:95]
	v_pk_mul_f32 v[154:155], v[8:9], v[154:155]
	v_pk_mul_f32 v[92:93], v[10:11], v[92:93]
	s_mov_b64 vcc, s[8:9]
	s_nop 0
	v_cndmask_b32_dpp v132, v154, v152, vcc quad_perm:[1,0,3,2] row_mask:0xf bank_mask:0xf
	v_cndmask_b32_dpp v133, v155, v153, vcc quad_perm:[1,0,3,2] row_mask:0xf bank_mask:0xf
	v_cndmask_b32_dpp v134, v92, v94, vcc quad_perm:[1,0,3,2] row_mask:0xf bank_mask:0xf
	v_cndmask_b32_dpp v135, v93, v95, vcc quad_perm:[1,0,3,2] row_mask:0xf bank_mask:0xf
	s_mov_b64 vcc, s[10:11]
	v_cndmask_b32_dpp v136, v152, v154, vcc quad_perm:[1,0,3,2] row_mask:0xf bank_mask:0xf
	v_cndmask_b32_dpp v137, v153, v155, vcc quad_perm:[1,0,3,2] row_mask:0xf bank_mask:0xf
	v_cndmask_b32_dpp v138, v94, v92, vcc quad_perm:[1,0,3,2] row_mask:0xf bank_mask:0xf
	v_cndmask_b32_dpp v139, v95, v93, vcc quad_perm:[1,0,3,2] row_mask:0xf bank_mask:0xf
	global_store_dwordx4 v[140:141], v[132:135], off offset:-2048
	global_store_dwordx4 v[140:141], v[136:139], off offset:2048
	v_pk_mul_f32 v[158:159], v[158:159], v[198:199] op_sel_hi:[1,0]
	v_pk_mul_f32 v[156:157], v[156:157], v[198:199] op_sel_hi:[1,0]
	v_pk_mul_f32 v[162:163], v[162:163], v[198:199] op_sel_hi:[1,0]
	v_pk_mul_f32 v[160:161], v[160:161], v[198:199] op_sel_hi:[1,0]
	v_pk_mul_f32 v[158:159], v[4:5], v[158:159]
	v_pk_mul_f32 v[156:157], v[6:7], v[156:157]
	v_pk_mul_f32 v[162:163], v[0:1], v[162:163]
	v_pk_mul_f32 v[160:161], v[2:3], v[160:161]
	s_mov_b64 vcc, s[8:9]
	s_nop 0
	v_cndmask_b32_dpp v132, v162, v158, vcc quad_perm:[1,0,3,2] row_mask:0xf bank_mask:0xf
	v_cndmask_b32_dpp v133, v163, v159, vcc quad_perm:[1,0,3,2] row_mask:0xf bank_mask:0xf
	v_cndmask_b32_dpp v134, v160, v156, vcc quad_perm:[1,0,3,2] row_mask:0xf bank_mask:0xf
	v_cndmask_b32_dpp v135, v161, v157, vcc quad_perm:[1,0,3,2] row_mask:0xf bank_mask:0xf
	s_mov_b64 vcc, s[10:11]
	v_cndmask_b32_dpp v136, v158, v162, vcc quad_perm:[1,0,3,2] row_mask:0xf bank_mask:0xf
	v_cndmask_b32_dpp v137, v159, v163, vcc quad_perm:[1,0,3,2] row_mask:0xf bank_mask:0xf
	v_cndmask_b32_dpp v138, v156, v160, vcc quad_perm:[1,0,3,2] row_mask:0xf bank_mask:0xf
	v_cndmask_b32_dpp v139, v157, v161, vcc quad_perm:[1,0,3,2] row_mask:0xf bank_mask:0xf
	global_store_dwordx4 v[140:141], v[132:135], off offset:-1536
	global_store_dwordx4 v[140:141], v[136:139], off offset:2560
	v_lshl_add_u64 v[140:141], v[140:141], 0, s[12:13]
	v_mov_b32_e32 v198, v189
	v_pk_mul_f32 v[166:167], v[166:167], v[198:199] op_sel_hi:[1,0]
	v_pk_mul_f32 v[146:147], v[146:147], v[198:199] op_sel_hi:[1,0]
	v_pk_mul_f32 v[174:175], v[174:175], v[198:199] op_sel_hi:[1,0]
	v_pk_mul_f32 v[148:149], v[148:149], v[198:199] op_sel_hi:[1,0]
	v_pk_mul_f32 v[166:167], v[12:13], v[166:167]
	v_pk_mul_f32 v[146:147], v[14:15], v[146:147]
	v_pk_mul_f32 v[174:175], v[8:9], v[174:175]
	v_pk_mul_f32 v[148:149], v[10:11], v[148:149]
	s_mov_b64 vcc, s[8:9]
	s_nop 0
	v_cndmask_b32_dpp v132, v174, v166, vcc quad_perm:[1,0,3,2] row_mask:0xf bank_mask:0xf
	v_cndmask_b32_dpp v133, v175, v167, vcc quad_perm:[1,0,3,2] row_mask:0xf bank_mask:0xf
	v_cndmask_b32_dpp v134, v148, v146, vcc quad_perm:[1,0,3,2] row_mask:0xf bank_mask:0xf
	v_cndmask_b32_dpp v135, v149, v147, vcc quad_perm:[1,0,3,2] row_mask:0xf bank_mask:0xf
	s_mov_b64 vcc, s[10:11]
	v_cndmask_b32_dpp v136, v166, v174, vcc quad_perm:[1,0,3,2] row_mask:0xf bank_mask:0xf
	v_cndmask_b32_dpp v137, v167, v175, vcc quad_perm:[1,0,3,2] row_mask:0xf bank_mask:0xf
	v_cndmask_b32_dpp v138, v146, v148, vcc quad_perm:[1,0,3,2] row_mask:0xf bank_mask:0xf
	v_cndmask_b32_dpp v139, v147, v149, vcc quad_perm:[1,0,3,2] row_mask:0xf bank_mask:0xf
	global_store_dwordx4 v[140:141], v[132:135], off offset:-2048
	global_store_dwordx4 v[140:141], v[136:139], off offset:2048
	v_pk_mul_f32 v[176:177], v[176:177], v[198:199] op_sel_hi:[1,0]
	v_pk_mul_f32 v[164:165], v[164:165], v[198:199] op_sel_hi:[1,0]
	v_pk_mul_f32 v[180:181], v[180:181], v[198:199] op_sel_hi:[1,0]
	v_pk_mul_f32 v[150:151], v[150:151], v[198:199] op_sel_hi:[1,0]
	v_pk_mul_f32 v[176:177], v[4:5], v[176:177]
	v_pk_mul_f32 v[164:165], v[6:7], v[164:165]
	v_pk_mul_f32 v[180:181], v[0:1], v[180:181]
	v_pk_mul_f32 v[150:151], v[2:3], v[150:151]
	s_mov_b64 vcc, s[8:9]
	s_nop 0
	v_cndmask_b32_dpp v132, v180, v176, vcc quad_perm:[1,0,3,2] row_mask:0xf bank_mask:0xf
	v_cndmask_b32_dpp v133, v181, v177, vcc quad_perm:[1,0,3,2] row_mask:0xf bank_mask:0xf
	v_cndmask_b32_dpp v134, v150, v164, vcc quad_perm:[1,0,3,2] row_mask:0xf bank_mask:0xf
; __device__ __forceinline__ void st_bf16x8(bf16_t* p, const f32x4 a, const f32x4 b) { uint4 o; o.x = cvt_pk_bf16(a[0], a[1]); o.y = cvt_pk_bf16(a[2], a[3]); o.z = cvt_pk_bf16(b[0], b[1]); o.w = cvt_pk_bf16(b[2], b[3]); *(uint4*)p = o; }
;     __device__ __forceinline__ void fused(f32x4 (&acc)[2][2][4][2], const Unit& u, int wr, int wc, int fr, int fq, float* smem) const {
;     ...
; #pragma unroll
;         for (int ai = 0; ai < 2; ++ai)
; #pragma unroll
;             for (int m = 0; m < 4; ++m) { const int rl = rl0 + ai * HALF + m * 16; const size_t ro = (size_t)(u.pm * BM + rl) * DM; const float r = rsv[rl];
; #pragma unroll
;                 for (int bj = 0; bj < 2; ++bj) { const int c = cb + bj * HALF; const f32x4 v0 = acc[ai][bj][m][0], v1 = acc[ai][bj][m][1];
;                     if (MODE == 0) { st_bf16x8(X1 + ro + c, v0, v1); st_bf16x8(H + ro + c, v0 * r * gs[bj][0] + sh[bj][0], v1 * r * gs[bj][1] + sh[bj][1]); }
;                     else { *(f32x4*)(out + ro + c) = v0 * r * gs[bj][0]; *(f32x4*)(out + ro + c + 4) = v1 * r * gs[bj][1]; } } }
	v_cndmask_b32_dpp v135, v151, v165, vcc quad_perm:[1,0,3,2] row_mask:0xf bank_mask:0xf
	s_mov_b64 vcc, s[10:11]
	v_cndmask_b32_dpp v136, v176, v180, vcc quad_perm:[1,0,3,2] row_mask:0xf bank_mask:0xf
	v_cndmask_b32_dpp v137, v177, v181, vcc quad_perm:[1,0,3,2] row_mask:0xf bank_mask:0xf
	v_cndmask_b32_dpp v138, v164, v150, vcc quad_perm:[1,0,3,2] row_mask:0xf bank_mask:0xf
	v_cndmask_b32_dpp v139, v165, v151, vcc quad_perm:[1,0,3,2] row_mask:0xf bank_mask:0xf
	global_store_dwordx4 v[140:141], v[132:135], off offset:-1536
	global_store_dwordx4 v[140:141], v[136:139], off offset:2560
	v_lshl_add_u64 v[140:141], v[140:141], 0, s[14:15]
	v_mov_b32_e32 v198, v190
	v_pk_mul_f32 v[60:61], v[60:61], v[198:199] op_sel_hi:[1,0]
	v_pk_mul_f32 v[62:63], v[62:63], v[198:199] op_sel_hi:[1,0]
	v_pk_mul_f32 v[56:57], v[56:57], v[198:199] op_sel_hi:[1,0]
	v_pk_mul_f32 v[58:59], v[58:59], v[198:199] op_sel_hi:[1,0]
	v_pk_mul_f32 v[60:61], v[12:13], v[60:61]
	v_pk_mul_f32 v[62:63], v[14:15], v[62:63]
	v_pk_mul_f32 v[56:57], v[8:9], v[56:57]
	v_pk_mul_f32 v[58:59], v[10:11], v[58:59]
	s_mov_b64 vcc, s[8:9]
	s_nop 0
	v_cndmask_b32_dpp v132, v56, v60, vcc quad_perm:[1,0,3,2] row_mask:0xf bank_mask:0xf
	v_cndmask_b32_dpp v133, v57, v61, vcc quad_perm:[1,0,3,2] row_mask:0xf bank_mask:0xf
	v_cndmask_b32_dpp v134, v58, v62, vcc quad_perm:[1,0,3,2] row_mask:0xf bank_mask:0xf
	v_cndmask_b32_dpp v135, v59, v63, vcc quad_perm:[1,0,3,2] row_mask:0xf bank_mask:0xf
	s_mov_b64 vcc, s[10:11]
	v_cndmask_b32_dpp v136, v60, v56, vcc quad_perm:[1,0,3,2] row_mask:0xf bank_mask:0xf
	v_cndmask_b32_dpp v137, v61, v57, vcc quad_perm:[1,0,3,2] row_mask:0xf bank_mask:0xf
	v_cndmask_b32_dpp v138, v62, v58, vcc quad_perm:[1,0,3,2] row_mask:0xf bank_mask:0xf
	v_cndmask_b32_dpp v139, v63, v59, vcc quad_perm:[1,0,3,2] row_mask:0xf bank_mask:0xf
	global_store_dwordx4 v[140:141], v[132:135], off offset:-2048
	global_store_dwordx4 v[140:141], v[136:139], off offset:2048
	v_pk_mul_f32 v[52:53], v[52:53], v[198:199] op_sel_hi:[1,0]
	v_pk_mul_f32 v[54:55], v[54:55], v[198:199] op_sel_hi:[1,0]
	v_pk_mul_f32 v[48:49], v[48:49], v[198:199] op_sel_hi:[1,0]
	v_pk_mul_f32 v[50:51], v[50:51], v[198:199] op_sel_hi:[1,0]
	v_pk_mul_f32 v[52:53], v[4:5], v[52:53]
	v_pk_mul_f32 v[54:55], v[6:7], v[54:55]
	v_pk_mul_f32 v[48:49], v[0:1], v[48:49]
	v_pk_mul_f32 v[50:51], v[2:3], v[50:51]
	s_mov_b64 vcc, s[8:9]
	s_nop 0
	v_cndmask_b32_dpp v132, v48, v52, vcc quad_perm:[1,0,3,2] row_mask:0xf bank_mask:0xf
	v_cndmask_b32_dpp v133, v49, v53, vcc quad_perm:[1,0,3,2] row_mask:0xf bank_mask:0xf
	v_cndmask_b32_dpp v134, v50, v54, vcc quad_perm:[1,0,3,2] row_mask:0xf bank_mask:0xf
	v_cndmask_b32_dpp v135, v51, v55, vcc quad_perm:[1,0,3,2] row_mask:0xf bank_mask:0xf
	s_mov_b64 vcc, s[10:11]
	v_cndmask_b32_dpp v136, v52, v48, vcc quad_perm:[1,0,3,2] row_mask:0xf bank_mask:0xf
	v_cndmask_b32_dpp v137, v53, v49, vcc quad_perm:[1,0,3,2] row_mask:0xf bank_mask:0xf
	v_cndmask_b32_dpp v138, v54, v50, vcc quad_perm:[1,0,3,2] row_mask:0xf bank_mask:0xf
	v_cndmask_b32_dpp v139, v55, v51, vcc quad_perm:[1,0,3,2] row_mask:0xf bank_mask:0xf
	global_store_dwordx4 v[140:141], v[132:135], off offset:-1536
	global_store_dwordx4 v[140:141], v[136:139], off offset:2560
	v_lshl_add_u64 v[140:141], v[140:141], 0, s[12:13]
	v_mov_b32_e32 v198, v191
	v_pk_mul_f32 v[44:45], v[44:45], v[198:199] op_sel_hi:[1,0]
	v_pk_mul_f32 v[46:47], v[46:47], v[198:199] op_sel_hi:[1,0]
	v_pk_mul_f32 v[40:41], v[40:41], v[198:199] op_sel_hi:[1,0]
	v_pk_mul_f32 v[42:43], v[42:43], v[198:199] op_sel_hi:[1,0]
	v_pk_mul_f32 v[44:45], v[12:13], v[44:45]
	v_pk_mul_f32 v[46:47], v[14:15], v[46:47]
	v_pk_mul_f32 v[40:41], v[8:9], v[40:41]
	v_pk_mul_f32 v[42:43], v[10:11], v[42:43]
	s_mov_b64 vcc, s[8:9]
	s_nop 0
	v_cndmask_b32_dpp v132, v40, v44, vcc quad_perm:[1,0,3,2] row_mask:0xf bank_mask:0xf
	v_cndmask_b32_dpp v133, v41, v45, vcc quad_perm:[1,0,3,2] row_mask:0xf bank_mask:0xf
	v_cndmask_b32_dpp v134, v42, v46, vcc quad_perm:[1,0,3,2] row_mask:0xf bank_mask:0xf
	v_cndmask_b32_dpp v135, v43, v47, vcc quad_perm:[1,0,3,2] row_mask:0xf bank_mask:0xf
	s_mov_b64 vcc, s[10:11]
	v_cndmask_b32_dpp v136, v44, v40, vcc quad_perm:[1,0,3,2] row_mask:0xf bank_mask:0xf
	v_cndmask_b32_dpp v137, v45, v41, vcc quad_perm:[1,0,3,2] row_mask:0xf bank_mask:0xf
	v_cndmask_b32_dpp v138, v46, v42, vcc quad_perm:[1,0,3,2] row_mask:0xf bank_mask:0xf
	v_cndmask_b32_dpp v139, v47, v43, vcc quad_perm:[1,0,3,2] row_mask:0xf bank_mask:0xf
	global_store_dwordx4 v[140:141], v[132:135], off offset:-2048
	global_store_dwordx4 v[140:141], v[136:139], off offset:2048
	v_pk_mul_f32 v[36:37], v[36:37], v[198:199] op_sel_hi:[1,0]
	v_pk_mul_f32 v[38:39], v[38:39], v[198:199] op_sel_hi:[1,0]
	v_pk_mul_f32 v[32:33], v[32:33], v[198:199] op_sel_hi:[1,0]
	v_pk_mul_f32 v[34:35], v[34:35], v[198:199] op_sel_hi:[1,0]
	v_pk_mul_f32 v[36:37], v[4:5], v[36:37]
	v_pk_mul_f32 v[38:39], v[6:7], v[38:39]
	v_pk_mul_f32 v[32:33], v[0:1], v[32:33]
	v_pk_mul_f32 v[34:35], v[2:3], v[34:35]
	s_mov_b64 vcc, s[8:9]
	s_nop 0
	v_cndmask_b32_dpp v132, v32, v36, vcc quad_perm:[1,0,3,2] row_mask:0xf bank_mask:0xf
	v_cndmask_b32_dpp v133, v33, v37, vcc quad_perm:[1,0,3,2] row_mask:0xf bank_mask:0xf
	v_cndmask_b32_dpp v134, v34, v38, vcc quad_perm:[1,0,3,2] row_mask:0xf bank_mask:0xf
	v_cndmask_b32_dpp v135, v35, v39, vcc quad_perm:[1,0,3,2] row_mask:0xf bank_mask:0xf
	s_mov_b64 vcc, s[10:11]
	v_cndmask_b32_dpp v136, v36, v32, vcc quad_perm:[1,0,3,2] row_mask:0xf bank_mask:0xf
	v_cndmask_b32_dpp v137, v37, v33, vcc quad_perm:[1,0,3,2] row_mask:0xf bank_mask:0xf
; __device__ __forceinline__ void st_bf16x8(bf16_t* p, const f32x4 a, const f32x4 b) { uint4 o; o.x = cvt_pk_bf16(a[0], a[1]); o.y = cvt_pk_bf16(a[2], a[3]); o.z = cvt_pk_bf16(b[0], b[1]); o.w = cvt_pk_bf16(b[2], b[3]); *(uint4*)p = o; }
;     __device__ __forceinline__ void fused(f32x4 (&acc)[2][2][4][2], const Unit& u, int wr, int wc, int fr, int fq, float* smem) const {
;     ...
; #pragma unroll
;         for (int ai = 0; ai < 2; ++ai)
; #pragma unroll
;             for (int m = 0; m < 4; ++m) { const int rl = rl0 + ai * HALF + m * 16; const size_t ro = (size_t)(u.pm * BM + rl) * DM; const float r = rsv[rl];
; #pragma unroll
;                 for (int bj = 0; bj < 2; ++bj) { const int c = cb + bj * HALF; const f32x4 v0 = acc[ai][bj][m][0], v1 = acc[ai][bj][m][1];
;                     if (MODE == 0) { st_bf16x8(X1 + ro + c, v0, v1); st_bf16x8(H + ro + c, v0 * r * gs[bj][0] + sh[bj][0], v1 * r * gs[bj][1] + sh[bj][1]); }
;                     else { *(f32x4*)(out + ro + c) = v0 * r * gs[bj][0]; *(f32x4*)(out + ro + c + 4) = v1 * r * gs[bj][1]; } } }
;         __syncthreads();
	v_cndmask_b32_dpp v138, v38, v34, vcc quad_perm:[1,0,3,2] row_mask:0xf bank_mask:0xf
	v_cndmask_b32_dpp v139, v39, v35, vcc quad_perm:[1,0,3,2] row_mask:0xf bank_mask:0xf
	global_store_dwordx4 v[140:141], v[132:135], off offset:-1536
	global_store_dwordx4 v[140:141], v[136:139], off offset:2560
	v_lshl_add_u64 v[140:141], v[140:141], 0, s[12:13]
	v_mov_b32_e32 v198, v192
	v_pk_mul_f32 v[28:29], v[28:29], v[198:199] op_sel_hi:[1,0]
	v_pk_mul_f32 v[30:31], v[30:31], v[198:199] op_sel_hi:[1,0]
	v_pk_mul_f32 v[24:25], v[24:25], v[198:199] op_sel_hi:[1,0]
	v_pk_mul_f32 v[26:27], v[26:27], v[198:199] op_sel_hi:[1,0]
	v_pk_mul_f32 v[28:29], v[12:13], v[28:29]
	v_pk_mul_f32 v[30:31], v[14:15], v[30:31]
	v_pk_mul_f32 v[24:25], v[8:9], v[24:25]
	v_pk_mul_f32 v[26:27], v[10:11], v[26:27]
	s_mov_b64 vcc, s[8:9]
	s_nop 0
	v_cndmask_b32_dpp v132, v24, v28, vcc quad_perm:[1,0,3,2] row_mask:0xf bank_mask:0xf
	v_cndmask_b32_dpp v133, v25, v29, vcc quad_perm:[1,0,3,2] row_mask:0xf bank_mask:0xf
	v_cndmask_b32_dpp v134, v26, v30, vcc quad_perm:[1,0,3,2] row_mask:0xf bank_mask:0xf
	v_cndmask_b32_dpp v135, v27, v31, vcc quad_perm:[1,0,3,2] row_mask:0xf bank_mask:0xf
	s_mov_b64 vcc, s[10:11]
	v_cndmask_b32_dpp v136, v28, v24, vcc quad_perm:[1,0,3,2] row_mask:0xf bank_mask:0xf
	v_cndmask_b32_dpp v137, v29, v25, vcc quad_perm:[1,0,3,2] row_mask:0xf bank_mask:0xf
	v_cndmask_b32_dpp v138, v30, v26, vcc quad_perm:[1,0,3,2] row_mask:0xf bank_mask:0xf
	v_cndmask_b32_dpp v139, v31, v27, vcc quad_perm:[1,0,3,2] row_mask:0xf bank_mask:0xf
	global_store_dwordx4 v[140:141], v[132:135], off offset:-2048
	global_store_dwordx4 v[140:141], v[136:139], off offset:2048
	v_pk_mul_f32 v[20:21], v[20:21], v[198:199] op_sel_hi:[1,0]
	v_pk_mul_f32 v[22:23], v[22:23], v[198:199] op_sel_hi:[1,0]
	v_pk_mul_f32 v[16:17], v[16:17], v[198:199] op_sel_hi:[1,0]
	v_pk_mul_f32 v[18:19], v[18:19], v[198:199] op_sel_hi:[1,0]
	v_pk_mul_f32 v[20:21], v[4:5], v[20:21]
	v_pk_mul_f32 v[22:23], v[6:7], v[22:23]
	v_pk_mul_f32 v[16:17], v[0:1], v[16:17]
	v_pk_mul_f32 v[18:19], v[2:3], v[18:19]
	s_mov_b64 vcc, s[8:9]
	s_nop 0
	v_cndmask_b32_dpp v132, v16, v20, vcc quad_perm:[1,0,3,2] row_mask:0xf bank_mask:0xf
	v_cndmask_b32_dpp v133, v17, v21, vcc quad_perm:[1,0,3,2] row_mask:0xf bank_mask:0xf
	v_cndmask_b32_dpp v134, v18, v22, vcc quad_perm:[1,0,3,2] row_mask:0xf bank_mask:0xf
	v_cndmask_b32_dpp v135, v19, v23, vcc quad_perm:[1,0,3,2] row_mask:0xf bank_mask:0xf
	s_mov_b64 vcc, s[10:11]
	v_cndmask_b32_dpp v136, v20, v16, vcc quad_perm:[1,0,3,2] row_mask:0xf bank_mask:0xf
	v_cndmask_b32_dpp v137, v21, v17, vcc quad_perm:[1,0,3,2] row_mask:0xf bank_mask:0xf
	v_cndmask_b32_dpp v138, v22, v18, vcc quad_perm:[1,0,3,2] row_mask:0xf bank_mask:0xf
	v_cndmask_b32_dpp v139, v23, v19, vcc quad_perm:[1,0,3,2] row_mask:0xf bank_mask:0xf
	global_store_dwordx4 v[140:141], v[132:135], off offset:-1536
	global_store_dwordx4 v[140:141], v[136:139], off offset:2560
	v_lshl_add_u64 v[140:141], v[140:141], 0, s[12:13]
	v_mov_b32_e32 v198, v193
	v_pk_mul_f32 v[70:71], v[70:71], v[198:199] op_sel_hi:[1,0]
	v_pk_mul_f32 v[64:65], v[64:65], v[198:199] op_sel_hi:[1,0]
	v_pk_mul_f32 v[72:73], v[72:73], v[198:199] op_sel_hi:[1,0]
	v_pk_mul_f32 v[66:67], v[66:67], v[198:199] op_sel_hi:[1,0]
	v_pk_mul_f32 v[70:71], v[12:13], v[70:71]
	v_pk_mul_f32 v[64:65], v[14:15], v[64:65]
	v_pk_mul_f32 v[72:73], v[8:9], v[72:73]
	v_pk_mul_f32 v[66:67], v[10:11], v[66:67]
	s_mov_b64 vcc, s[8:9]
	s_nop 0
	v_cndmask_b32_dpp v132, v72, v70, vcc quad_perm:[1,0,3,2] row_mask:0xf bank_mask:0xf
	v_cndmask_b32_dpp v133, v73, v71, vcc quad_perm:[1,0,3,2] row_mask:0xf bank_mask:0xf
	v_cndmask_b32_dpp v134, v66, v64, vcc quad_perm:[1,0,3,2] row_mask:0xf bank_mask:0xf
	v_cndmask_b32_dpp v135, v67, v65, vcc quad_perm:[1,0,3,2] row_mask:0xf bank_mask:0xf
	s_mov_b64 vcc, s[10:11]
	v_cndmask_b32_dpp v136, v70, v72, vcc quad_perm:[1,0,3,2] row_mask:0xf bank_mask:0xf
	v_cndmask_b32_dpp v137, v71, v73, vcc quad_perm:[1,0,3,2] row_mask:0xf bank_mask:0xf
	v_cndmask_b32_dpp v138, v64, v66, vcc quad_perm:[1,0,3,2] row_mask:0xf bank_mask:0xf
	v_cndmask_b32_dpp v139, v65, v67, vcc quad_perm:[1,0,3,2] row_mask:0xf bank_mask:0xf
	global_store_dwordx4 v[140:141], v[132:135], off offset:-2048
	global_store_dwordx4 v[140:141], v[136:139], off offset:2048
	v_pk_mul_f32 v[76:77], v[76:77], v[198:199] op_sel_hi:[1,0]
	v_pk_mul_f32 v[68:69], v[68:69], v[198:199] op_sel_hi:[1,0]
	v_pk_mul_f32 v[78:79], v[78:79], v[198:199] op_sel_hi:[1,0]
	v_pk_mul_f32 v[74:75], v[74:75], v[198:199] op_sel_hi:[1,0]
	v_pk_mul_f32 v[76:77], v[4:5], v[76:77]
	v_pk_mul_f32 v[68:69], v[6:7], v[68:69]
	v_pk_mul_f32 v[78:79], v[0:1], v[78:79]
	v_pk_mul_f32 v[74:75], v[2:3], v[74:75]
	s_mov_b64 vcc, s[8:9]
	s_nop 0
	v_cndmask_b32_dpp v132, v78, v76, vcc quad_perm:[1,0,3,2] row_mask:0xf bank_mask:0xf
	v_cndmask_b32_dpp v133, v79, v77, vcc quad_perm:[1,0,3,2] row_mask:0xf bank_mask:0xf
	v_cndmask_b32_dpp v134, v74, v68, vcc quad_perm:[1,0,3,2] row_mask:0xf bank_mask:0xf
	v_cndmask_b32_dpp v135, v75, v69, vcc quad_perm:[1,0,3,2] row_mask:0xf bank_mask:0xf
	s_mov_b64 vcc, s[10:11]
	v_cndmask_b32_dpp v136, v76, v78, vcc quad_perm:[1,0,3,2] row_mask:0xf bank_mask:0xf
	v_cndmask_b32_dpp v137, v77, v79, vcc quad_perm:[1,0,3,2] row_mask:0xf bank_mask:0xf
	v_cndmask_b32_dpp v138, v68, v74, vcc quad_perm:[1,0,3,2] row_mask:0xf bank_mask:0xf
	v_cndmask_b32_dpp v139, v69, v75, vcc quad_perm:[1,0,3,2] row_mask:0xf bank_mask:0xf
	global_store_dwordx4 v[140:141], v[132:135], off offset:-1536
	global_store_dwordx4 v[140:141], v[136:139], off offset:2560
	s_barrier
